# attn hoist, padded so GEMM loop offset = baseline+64B
# baseline (speedup 1.0000x reference)
; #define GAS __attribute__((address_space(1)))
; #define LAS __attribute__((address_space(3)))
; __device__ __forceinline__ unsigned cvtpk(float lo, float hi) { unsigned r; asm volatile("v_cvt_pk_bf16_f32 %0, %1, %2" : "=v"(r) : "v"(lo), "v"(hi)); return r; }
; __device__ __forceinline__ void attn_phase(LAS unsigned char* lds, const bf16* Qg, const bf16* Kg, const bf16* Vg  , bf16* OB, float* LSE, int g, int dsh, int u_lo, int u_hi) {
;     ...
;         for (int j4 = 0; j4 < 4; ++j4) { const int rr = rr0 + 8 * j4; v4u sv = *(const LAS v4u*)(Ost + rr * 136 + cc * 16);
;             if (g > 0) { const float ear = __shfl(ea, rr); const v4u pq = pv4[j4];
;                 sv.x = cvtpk(bflo(sv.x) + bflo(pq.x) * ear, bfhi(sv.x) + bfhi(pq.x) * ear); sv.y = cvtpk(bflo(sv.y) + bflo(pq.y) * ear, bfhi(sv.y) + bfhi(pq.y) * ear);
;                 sv.z = cvtpk(bflo(sv.z) + bflo(pq.z) * ear, bfhi(sv.z) + bfhi(pq.z) * ear); sv.w = cvtpk(bflo(sv.w) + bflo(pq.w) * ear, bfhi(sv.w) + bfhi(pq.w) * ear); }
;             *(GAS v4u*)(OB + (tokbase + (size_t)(Q0 + 32 * wave + rr) * dil) * 1024 + h * 64 + cc * 8) = sv; }
;         if (hh == 0) ((GAS float*)LSE)[qtok * 16 + h] = lse;
.LBB0_179:
	s_waitcnt lgkmcnt(0)
	v_or_b32_e32 v18, s78, v0
	v_ashrrev_i32_e32 v19, 31, v18
	v_lshlrev_b64 v[18:19], s30, v[18:19]
	v_lshl_add_u64 v[18:19], v[18:19], 0, s[62:63]
	v_lshlrev_b64 v[18:19], 11, v[18:19]
	v_lshl_add_u64 v[18:19], v[26:27], 0, v[18:19]
	v_cmp_gt_u32_e32 vcc, 32, v51
	global_store_dwordx4 v[18:19], v[22:25], off
	s_and_saveexec_b64 s[36:37], vcc
	s_cbranch_execz .LBB0_140
	s_lshl_b32 s94, s77, 2
	v_lshl_add_u64 v[18:19], v[48:49], 0, s[94:95]
	global_store_dword v[18:19], v50, off
	s_branch .LBB0_140
	s_nop 0
